# row-scale GEMM epilogues (in-proj, mem kv, SwiGLU): the 8 per-row-group scale loads prefetched together at epilogue start, per-group drains removed (s_nop keeps the 128-bit store data WAR wait states)
# speedup vs baseline: 1.0998x; 1.0049x over previous
.LBB0_305:
	v_lshl_add_u32 v144, s36, 8, v152
	v_ashrrev_i32_e32 v145, 31, v144
	v_lshl_add_u64 v[148:149], v[144:145], 2, s[18:19]
	s_waitcnt lgkmcnt(0)
	global_load_dword v226, v[148:149], off
	global_load_dword v227, v[148:149], off offset:64
	global_load_dword v228, v[148:149], off offset:128
	global_load_dword v229, v[148:149], off offset:192
	global_load_dword v230, v[148:149], off offset:512
	global_load_dword v231, v[148:149], off offset:576
	global_load_dword v232, v[148:149], off offset:640
	global_load_dword v233, v[148:149], off offset:704
	v_lshl_or_b32 v150, s57, 8, v154
	v_mov_b64_e32 v[146:147], s[16:17]
	v_ashrrev_i32_e32 v151, 31, v150
	v_mad_i64_i32 v[162:163], s[38:39], v144, s56, v[146:147]
	v_or_b32_e32 v164, 16, v144
	v_lshlrev_b64 v[150:151], 1, v[150:151]
	v_ashrrev_i32_e32 v165, 31, v164
	v_lshl_add_u64 v[162:163], v[162:163], 0, v[150:151]
	v_lshl_add_u64 v[166:167], v[164:165], 2, s[18:19]
	s_andn2_b64 vcc, exec, s[4:5]
	s_mov_b64 s[4:5], -1
	s_waitcnt vmcnt(0)
	v_mov_b32_e32 v160, v226
	v_pk_mul_f32 v[126:127], v[126:127], v[160:161] op_sel_hi:[1,0]
	v_pk_mul_f32 v[124:125], v[124:125], v[160:161] op_sel_hi:[1,0]
	v_pk_mul_f32 v[122:123], v[122:123], v[160:161] op_sel_hi:[1,0]
	v_pk_mul_f32 v[120:121], v[120:121], v[160:161] op_sel_hi:[1,0]
	v_pk_mul_f32 v[118:119], v[118:119], v[160:161] op_sel_hi:[1,0]
	v_pk_mul_f32 v[116:117], v[116:117], v[160:161] op_sel_hi:[1,0]
	v_pk_mul_f32 v[168:169], v[114:115], v[160:161] op_sel_hi:[1,0]
	v_pk_mul_f32 v[160:161], v[112:113], v[160:161] op_sel_hi:[1,0]
	v_cvt_pk_bf16_f32 v112, v124, v125
	v_cvt_pk_bf16_f32 v113, v126, v127
	v_cvt_pk_bf16_f32 v114, v120, v121
	v_cvt_pk_bf16_f32 v115, v122, v123
	global_store_dwordx4 v[162:163], v[112:115], off
	s_nop 1
	v_cvt_pk_bf16_f32 v112, v116, v117
	v_cvt_pk_bf16_f32 v113, v118, v119
	v_cvt_pk_bf16_f32 v114, v160, v161
	v_cvt_pk_bf16_f32 v115, v168, v169
	global_store_dwordx4 v[162:163], v[112:115], off offset:256
	s_nop 1
	v_mad_i64_i32 v[116:117], s[38:39], v164, s56, v[146:147]
	v_or_b32_e32 v114, 32, v144
	v_ashrrev_i32_e32 v115, 31, v114
	v_lshl_add_u64 v[116:117], v[116:117], 0, v[150:151]
	v_lshl_add_u64 v[118:119], v[114:115], 2, s[18:19]
	v_mov_b32_e32 v112, v227
	v_pk_mul_f32 v[110:111], v[110:111], v[112:113] op_sel_hi:[1,0]
	v_pk_mul_f32 v[108:109], v[108:109], v[112:113] op_sel_hi:[1,0]
	v_pk_mul_f32 v[106:107], v[106:107], v[112:113] op_sel_hi:[1,0]
	v_pk_mul_f32 v[104:105], v[104:105], v[112:113] op_sel_hi:[1,0]
	v_pk_mul_f32 v[102:103], v[102:103], v[112:113] op_sel_hi:[1,0]
	v_pk_mul_f32 v[100:101], v[100:101], v[112:113] op_sel_hi:[1,0]
	v_pk_mul_f32 v[120:121], v[98:99], v[112:113] op_sel_hi:[1,0]
	v_pk_mul_f32 v[112:113], v[96:97], v[112:113] op_sel_hi:[1,0]
	v_cvt_pk_bf16_f32 v96, v108, v109
	v_cvt_pk_bf16_f32 v97, v110, v111
	v_cvt_pk_bf16_f32 v98, v104, v105
	v_cvt_pk_bf16_f32 v99, v106, v107
	global_store_dwordx4 v[116:117], v[96:99], off
	s_nop 1
	v_cvt_pk_bf16_f32 v96, v100, v101
	v_cvt_pk_bf16_f32 v97, v102, v103
	v_cvt_pk_bf16_f32 v98, v112, v113
	v_cvt_pk_bf16_f32 v99, v120, v121
	global_store_dwordx4 v[116:117], v[96:99], off offset:256
	s_nop 1
	v_mad_i64_i32 v[100:101], s[38:39], v114, s56, v[146:147]
	v_or_b32_e32 v98, 48, v144
	v_ashrrev_i32_e32 v99, 31, v98
	v_lshl_add_u64 v[100:101], v[100:101], 0, v[150:151]
	v_lshl_add_u64 v[102:103], v[98:99], 2, s[18:19]
	v_mov_b32_e32 v96, v228
	v_pk_mul_f32 v[94:95], v[94:95], v[96:97] op_sel_hi:[1,0]
	v_pk_mul_f32 v[92:93], v[92:93], v[96:97] op_sel_hi:[1,0]
	v_pk_mul_f32 v[90:91], v[90:91], v[96:97] op_sel_hi:[1,0]
	v_pk_mul_f32 v[88:89], v[88:89], v[96:97] op_sel_hi:[1,0]
	v_pk_mul_f32 v[82:83], v[82:83], v[96:97] op_sel_hi:[1,0]
	v_pk_mul_f32 v[80:81], v[80:81], v[96:97] op_sel_hi:[1,0]
	v_pk_mul_f32 v[104:105], v[74:75], v[96:97] op_sel_hi:[1,0]
	v_pk_mul_f32 v[96:97], v[72:73], v[96:97] op_sel_hi:[1,0]
	v_cvt_pk_bf16_f32 v72, v92, v93
	v_cvt_pk_bf16_f32 v73, v94, v95
	v_cvt_pk_bf16_f32 v74, v88, v89
	v_cvt_pk_bf16_f32 v75, v90, v91
	global_store_dwordx4 v[100:101], v[72:75], off
	s_nop 1
	v_cvt_pk_bf16_f32 v72, v80, v81
	v_cvt_pk_bf16_f32 v73, v82, v83
	v_cvt_pk_bf16_f32 v74, v96, v97
	v_cvt_pk_bf16_f32 v75, v104, v105
	global_store_dwordx4 v[100:101], v[72:75], off offset:256
	s_nop 1
	v_mov_b32_e32 v72, v229
	v_pk_mul_f32 v[80:81], v[86:87], v[72:73] op_sel_hi:[1,0]
	v_mad_i64_i32 v[74:75], s[38:39], v98, s56, v[146:147]
	v_lshl_add_u64 v[74:75], v[74:75], 0, v[150:151]
	v_pk_mul_f32 v[82:83], v[84:85], v[72:73] op_sel_hi:[1,0]
	v_pk_mul_f32 v[78:79], v[78:79], v[72:73] op_sel_hi:[1,0]
	v_pk_mul_f32 v[76:77], v[76:77], v[72:73] op_sel_hi:[1,0]
	v_pk_mul_f32 v[70:71], v[70:71], v[72:73] op_sel_hi:[1,0]
	v_pk_mul_f32 v[68:69], v[68:69], v[72:73] op_sel_hi:[1,0]
	v_pk_mul_f32 v[84:85], v[66:67], v[72:73] op_sel_hi:[1,0]
	v_pk_mul_f32 v[72:73], v[64:65], v[72:73] op_sel_hi:[1,0]
	v_cvt_pk_bf16_f32 v64, v82, v83
	v_cvt_pk_bf16_f32 v65, v80, v81
	v_cvt_pk_bf16_f32 v66, v76, v77
	v_cvt_pk_bf16_f32 v67, v78, v79
	global_store_dwordx4 v[74:75], v[64:67], off
	s_nop 1
	v_cvt_pk_bf16_f32 v64, v68, v69
	v_cvt_pk_bf16_f32 v65, v70, v71
	v_cvt_pk_bf16_f32 v66, v72, v73
	v_cvt_pk_bf16_f32 v67, v84, v85
	global_store_dwordx4 v[74:75], v[64:67], off offset:256
	s_nop 1
	s_nop 0
	v_add_u32_e32 v65, 0x80, v144
	v_mad_i64_i32 v[66:67], s[38:39], v65, s56, v[146:147]
	v_lshl_add_u64 v[66:67], v[66:67], 0, v[150:151]
	v_mov_b32_e32 v64, v230
	v_pk_mul_f32 v[62:63], v[62:63], v[64:65] op_sel_hi:[1,0]
	v_pk_mul_f32 v[60:61], v[60:61], v[64:65] op_sel_hi:[1,0]
	v_pk_mul_f32 v[58:59], v[58:59], v[64:65] op_sel_hi:[1,0]
	v_pk_mul_f32 v[56:57], v[56:57], v[64:65] op_sel_hi:[1,0]
	v_pk_mul_f32 v[54:55], v[54:55], v[64:65] op_sel_hi:[1,0]
	v_pk_mul_f32 v[52:53], v[52:53], v[64:65] op_sel_hi:[1,0]
	v_pk_mul_f32 v[68:69], v[50:51], v[64:65] op_sel_hi:[1,0]
	v_pk_mul_f32 v[64:65], v[48:49], v[64:65] op_sel_hi:[1,0]
	v_cvt_pk_bf16_f32 v48, v60, v61
	v_cvt_pk_bf16_f32 v49, v62, v63
	v_cvt_pk_bf16_f32 v50, v56, v57
	v_cvt_pk_bf16_f32 v51, v58, v59
	global_store_dwordx4 v[66:67], v[48:51], off
	s_nop 1
	v_cvt_pk_bf16_f32 v48, v52, v53
	v_cvt_pk_bf16_f32 v49, v54, v55
	v_cvt_pk_bf16_f32 v50, v64, v65
	v_cvt_pk_bf16_f32 v51, v68, v69
	global_store_dwordx4 v[66:67], v[48:51], off offset:256
	s_nop 1
	s_nop 0
	v_add_u32_e32 v49, 0x90, v144
	v_mad_i64_i32 v[50:51], s[38:39], v49, s56, v[146:147]
	v_lshl_add_u64 v[50:51], v[50:51], 0, v[150:151]
	v_mov_b32_e32 v48, v231
	v_pk_mul_f32 v[46:47], v[46:47], v[48:49] op_sel_hi:[1,0]
	v_pk_mul_f32 v[44:45], v[44:45], v[48:49] op_sel_hi:[1,0]
	v_pk_mul_f32 v[42:43], v[42:43], v[48:49] op_sel_hi:[1,0]
	v_pk_mul_f32 v[40:41], v[40:41], v[48:49] op_sel_hi:[1,0]
	v_pk_mul_f32 v[38:39], v[38:39], v[48:49] op_sel_hi:[1,0]
	v_pk_mul_f32 v[36:37], v[36:37], v[48:49] op_sel_hi:[1,0]
	v_pk_mul_f32 v[52:53], v[34:35], v[48:49] op_sel_hi:[1,0]
	v_pk_mul_f32 v[48:49], v[32:33], v[48:49] op_sel_hi:[1,0]
	v_cvt_pk_bf16_f32 v32, v44, v45
	v_cvt_pk_bf16_f32 v33, v46, v47
	v_cvt_pk_bf16_f32 v34, v40, v41
	v_cvt_pk_bf16_f32 v35, v42, v43
	global_store_dwordx4 v[50:51], v[32:35], off
	s_nop 1
	v_cvt_pk_bf16_f32 v32, v36, v37
	v_cvt_pk_bf16_f32 v33, v38, v39
	v_cvt_pk_bf16_f32 v34, v48, v49
	v_cvt_pk_bf16_f32 v35, v52, v53
	global_store_dwordx4 v[50:51], v[32:35], off offset:256
	s_nop 1
	s_nop 0
	v_add_u32_e32 v33, 0xa0, v144
	v_mad_i64_i32 v[34:35], s[38:39], v33, s56, v[146:147]
	v_lshl_add_u64 v[34:35], v[34:35], 0, v[150:151]
	v_mov_b32_e32 v32, v232
	v_pk_mul_f32 v[30:31], v[30:31], v[32:33] op_sel_hi:[1,0]
	v_pk_mul_f32 v[28:29], v[28:29], v[32:33] op_sel_hi:[1,0]
	v_pk_mul_f32 v[26:27], v[26:27], v[32:33] op_sel_hi:[1,0]
	v_pk_mul_f32 v[24:25], v[24:25], v[32:33] op_sel_hi:[1,0]
	v_pk_mul_f32 v[22:23], v[22:23], v[32:33] op_sel_hi:[1,0]
	v_pk_mul_f32 v[20:21], v[20:21], v[32:33] op_sel_hi:[1,0]
	v_pk_mul_f32 v[36:37], v[18:19], v[32:33] op_sel_hi:[1,0]
	v_pk_mul_f32 v[32:33], v[16:17], v[32:33] op_sel_hi:[1,0]
	v_cvt_pk_bf16_f32 v16, v28, v29
	v_cvt_pk_bf16_f32 v17, v30, v31
	v_cvt_pk_bf16_f32 v18, v24, v25
	v_cvt_pk_bf16_f32 v19, v26, v27
	global_store_dwordx4 v[34:35], v[16:19], off
	s_nop 1
	v_cvt_pk_bf16_f32 v16, v20, v21
	v_cvt_pk_bf16_f32 v17, v22, v23
	v_cvt_pk_bf16_f32 v18, v32, v33
	v_cvt_pk_bf16_f32 v19, v36, v37
	global_store_dwordx4 v[34:35], v[16:19], off offset:256
	s_nop 1
	s_nop 0
	v_add_u32_e32 v17, 0xb0, v144
	v_mad_i64_i32 v[18:19], s[38:39], v17, s56, v[146:147]
	v_lshl_add_u64 v[18:19], v[18:19], 0, v[150:151]
	v_mov_b32_e32 v16, v233
	v_pk_mul_f32 v[14:15], v[14:15], v[16:17] op_sel_hi:[1,0]
	v_pk_mul_f32 v[12:13], v[12:13], v[16:17] op_sel_hi:[1,0]
	v_pk_mul_f32 v[10:11], v[10:11], v[16:17] op_sel_hi:[1,0]
	v_pk_mul_f32 v[8:9], v[8:9], v[16:17] op_sel_hi:[1,0]
	v_pk_mul_f32 v[6:7], v[6:7], v[16:17] op_sel_hi:[1,0]
	v_pk_mul_f32 v[4:5], v[4:5], v[16:17] op_sel_hi:[1,0]
	v_pk_mul_f32 v[20:21], v[2:3], v[16:17] op_sel_hi:[1,0]
	v_pk_mul_f32 v[16:17], v[0:1], v[16:17] op_sel_hi:[1,0]
	v_cvt_pk_bf16_f32 v0, v12, v13
	v_cvt_pk_bf16_f32 v1, v14, v15
	v_cvt_pk_bf16_f32 v2, v8, v9
	v_cvt_pk_bf16_f32 v3, v10, v11
	global_store_dwordx4 v[18:19], v[0:3], off
	s_nop 1
	v_cvt_pk_bf16_f32 v0, v4, v5
	v_cvt_pk_bf16_f32 v1, v6, v7
	v_cvt_pk_bf16_f32 v2, v16, v17
	v_cvt_pk_bf16_f32 v3, v20, v21
	global_store_dwordx4 v[18:19], v[0:3], off offset:256
	s_cbranch_vccnz .LBB0_294
	s_andn2_b64 vcc, exec, s[8:9]
	s_cbranch_vccnz .LBB0_293
	s_barrier
	s_branch .LBB0_293

.LBB0_329:
	v_lshl_add_u32 v138, s30, 8, v144
	v_ashrrev_i32_e32 v139, 31, v138
	v_lshl_add_u64 v[142:143], v[138:139], 2, s[8:9]
	s_waitcnt lgkmcnt(0)
	global_load_dword v226, v[142:143], off
	global_load_dword v227, v[142:143], off offset:64
	global_load_dword v228, v[142:143], off offset:128
	global_load_dword v229, v[142:143], off offset:192
	global_load_dword v230, v[142:143], off offset:512
	global_load_dword v231, v[142:143], off offset:576
	global_load_dword v232, v[142:143], off offset:640
	global_load_dword v233, v[142:143], off offset:704
	s_lshl_b32 s21, s31, 8
	s_and_b32 s21, s21, 0x100
	s_cmp_lt_u32 s31, 2
	v_or_b32_e32 v140, s21, v146
	s_cselect_b32 s21, s57, 0x4600000
	s_cselect_b32 s23, s58, 0x1e30000
	s_add_u32 s36, s12, s21
	s_addc_u32 s37, s13, 0
	v_lshlrev_b64 v[154:155], 11, v[138:139]
	s_add_u32 s30, s14, s23
	v_lshlrev_b64 v[158:159], 10, v[138:139]
	v_lshlrev_b32_e32 v132, 2, v140
	v_lshl_add_u64 v[154:155], s[36:37], 0, v[154:155]
	s_addc_u32 s31, s15, 0
	v_mov_b32_e32 v141, v133
	v_lshlrev_b32_e32 v140, 1, v140
	v_lshl_add_u64 v[154:155], v[154:155], 0, v[132:133]
	v_lshl_add_u64 v[158:159], s[30:31], 0, v[158:159]
	v_lshl_add_u64 v[158:159], v[158:159], 0, v[140:141]
	v_or_b32_e32 v152, 16, v138
	v_ashrrev_i32_e32 v153, 31, v152
	v_lshl_add_u64 v[160:161], v[152:153], 2, s[8:9]
	s_andn2_b64 vcc, exec, s[24:25]
	s_mov_b64 s[24:25], -1
	s_waitcnt vmcnt(0)
	v_mov_b32_e32 v150, v226
	v_pk_mul_f32 v[126:127], v[126:127], v[150:151] op_sel_hi:[1,0]
	v_pk_mul_f32 v[124:125], v[124:125], v[150:151] op_sel_hi:[1,0]
	v_pk_mul_f32 v[120:121], v[120:121], v[150:151] op_sel_hi:[1,0]
	global_store_dwordx4 v[154:155], v[124:127], off
	v_pk_mul_f32 v[122:123], v[122:123], v[150:151] op_sel_hi:[1,0]
	v_pk_mul_f32 v[116:117], v[116:117], v[150:151] op_sel_hi:[1,0]
	v_cvt_pk_bf16_f32 v124, v124, v125
	v_cvt_pk_bf16_f32 v125, v126, v127
	global_store_dwordx2 v[158:159], v[124:125], off
	global_store_dwordx4 v[154:155], v[120:123], off offset:64
	v_pk_mul_f32 v[118:119], v[118:119], v[150:151] op_sel_hi:[1,0]
	v_pk_mul_f32 v[112:113], v[112:113], v[150:151] op_sel_hi:[1,0]
	v_cvt_pk_bf16_f32 v120, v120, v121
	v_cvt_pk_bf16_f32 v121, v122, v123
	global_store_dwordx2 v[158:159], v[120:121], off offset:32
	global_store_dwordx4 v[154:155], v[116:119], off offset:512
	v_pk_mul_f32 v[114:115], v[114:115], v[150:151] op_sel_hi:[1,0]
	s_nop 0
	v_cvt_pk_bf16_f32 v116, v116, v117
	v_cvt_pk_bf16_f32 v117, v118, v119
	global_store_dwordx2 v[158:159], v[116:117], off offset:256
	global_store_dwordx4 v[154:155], v[112:115], off offset:576
	v_lshlrev_b64 v[116:117], 11, v[152:153]
	v_lshlrev_b64 v[118:119], 10, v[152:153]
	v_cvt_pk_bf16_f32 v112, v112, v113
	v_cvt_pk_bf16_f32 v113, v114, v115
	global_store_dwordx2 v[158:159], v[112:113], off offset:288
	s_nop 1
	v_lshl_add_u64 v[116:117], s[36:37], 0, v[116:117]
	v_lshl_add_u64 v[116:117], v[116:117], 0, v[132:133]
	v_lshl_add_u64 v[118:119], s[30:31], 0, v[118:119]
	v_lshl_add_u64 v[118:119], v[118:119], 0, v[140:141]
	v_or_b32_e32 v114, 32, v138
	v_ashrrev_i32_e32 v115, 31, v114
	v_lshl_add_u64 v[120:121], v[114:115], 2, s[8:9]
	v_mov_b32_e32 v112, v227
	v_pk_mul_f32 v[110:111], v[110:111], v[112:113] op_sel_hi:[1,0]
	v_pk_mul_f32 v[108:109], v[108:109], v[112:113] op_sel_hi:[1,0]
	v_pk_mul_f32 v[104:105], v[104:105], v[112:113] op_sel_hi:[1,0]
	global_store_dwordx4 v[116:117], v[108:111], off
	v_pk_mul_f32 v[106:107], v[106:107], v[112:113] op_sel_hi:[1,0]
	v_pk_mul_f32 v[100:101], v[100:101], v[112:113] op_sel_hi:[1,0]
	v_cvt_pk_bf16_f32 v108, v108, v109
	v_cvt_pk_bf16_f32 v109, v110, v111
	global_store_dwordx2 v[118:119], v[108:109], off
	global_store_dwordx4 v[116:117], v[104:107], off offset:64
	v_pk_mul_f32 v[102:103], v[102:103], v[112:113] op_sel_hi:[1,0]
	v_pk_mul_f32 v[96:97], v[96:97], v[112:113] op_sel_hi:[1,0]
	v_cvt_pk_bf16_f32 v104, v104, v105
	v_cvt_pk_bf16_f32 v105, v106, v107
	global_store_dwordx2 v[118:119], v[104:105], off offset:32
	global_store_dwordx4 v[116:117], v[100:103], off offset:512
	v_pk_mul_f32 v[98:99], v[98:99], v[112:113] op_sel_hi:[1,0]
	s_nop 0
	v_cvt_pk_bf16_f32 v100, v100, v101
	v_cvt_pk_bf16_f32 v101, v102, v103
	global_store_dwordx2 v[118:119], v[100:101], off offset:256
	global_store_dwordx4 v[116:117], v[96:99], off offset:576
	v_lshlrev_b64 v[100:101], 11, v[114:115]
	v_lshlrev_b64 v[102:103], 10, v[114:115]
	v_cvt_pk_bf16_f32 v96, v96, v97
	v_cvt_pk_bf16_f32 v97, v98, v99
	global_store_dwordx2 v[118:119], v[96:97], off offset:288
	s_nop 1
	v_lshl_add_u64 v[100:101], s[36:37], 0, v[100:101]
	v_lshl_add_u64 v[100:101], v[100:101], 0, v[132:133]
	v_lshl_add_u64 v[102:103], s[30:31], 0, v[102:103]
	v_lshl_add_u64 v[102:103], v[102:103], 0, v[140:141]
	v_or_b32_e32 v98, 48, v138
	v_ashrrev_i32_e32 v99, 31, v98
	v_lshl_add_u64 v[104:105], v[98:99], 2, s[8:9]
	v_mov_b32_e32 v96, v228
	v_pk_mul_f32 v[94:95], v[94:95], v[96:97] op_sel_hi:[1,0]
	v_pk_mul_f32 v[92:93], v[92:93], v[96:97] op_sel_hi:[1,0]
	v_pk_mul_f32 v[88:89], v[88:89], v[96:97] op_sel_hi:[1,0]
	global_store_dwordx4 v[100:101], v[92:95], off
	v_pk_mul_f32 v[90:91], v[90:91], v[96:97] op_sel_hi:[1,0]
	v_pk_mul_f32 v[84:85], v[84:85], v[96:97] op_sel_hi:[1,0]
	v_cvt_pk_bf16_f32 v92, v92, v93
	v_cvt_pk_bf16_f32 v93, v94, v95
	global_store_dwordx2 v[102:103], v[92:93], off
	global_store_dwordx4 v[100:101], v[88:91], off offset:64
	v_pk_mul_f32 v[86:87], v[86:87], v[96:97] op_sel_hi:[1,0]
	v_pk_mul_f32 v[80:81], v[80:81], v[96:97] op_sel_hi:[1,0]
	v_cvt_pk_bf16_f32 v88, v88, v89
	v_cvt_pk_bf16_f32 v89, v90, v91
	global_store_dwordx2 v[102:103], v[88:89], off offset:32
	global_store_dwordx4 v[100:101], v[84:87], off offset:512
	v_pk_mul_f32 v[82:83], v[82:83], v[96:97] op_sel_hi:[1,0]
	s_nop 0
	v_cvt_pk_bf16_f32 v84, v84, v85
	v_cvt_pk_bf16_f32 v85, v86, v87
	global_store_dwordx2 v[102:103], v[84:85], off offset:256
	global_store_dwordx4 v[100:101], v[80:83], off offset:576
	v_lshlrev_b64 v[84:85], 10, v[98:99]
	v_lshl_add_u64 v[84:85], s[30:31], 0, v[84:85]
	v_cvt_pk_bf16_f32 v80, v80, v81
	v_cvt_pk_bf16_f32 v81, v82, v83
	global_store_dwordx2 v[102:103], v[80:81], off offset:288
	s_nop 1
	v_lshlrev_b64 v[82:83], 11, v[98:99]
	v_lshl_add_u64 v[82:83], s[36:37], 0, v[82:83]
	v_lshl_add_u64 v[82:83], v[82:83], 0, v[132:133]
	v_lshl_add_u64 v[84:85], v[84:85], 0, v[140:141]
	v_mov_b32_e32 v80, v229
	v_pk_mul_f32 v[78:79], v[78:79], v[80:81] op_sel_hi:[1,0]
	v_pk_mul_f32 v[76:77], v[76:77], v[80:81] op_sel_hi:[1,0]
	v_pk_mul_f32 v[72:73], v[72:73], v[80:81] op_sel_hi:[1,0]
	global_store_dwordx4 v[82:83], v[76:79], off
	v_pk_mul_f32 v[74:75], v[74:75], v[80:81] op_sel_hi:[1,0]
	v_pk_mul_f32 v[68:69], v[68:69], v[80:81] op_sel_hi:[1,0]
	v_cvt_pk_bf16_f32 v76, v76, v77
	v_cvt_pk_bf16_f32 v77, v78, v79
	global_store_dwordx2 v[84:85], v[76:77], off
	global_store_dwordx4 v[82:83], v[72:75], off offset:64
	v_pk_mul_f32 v[70:71], v[70:71], v[80:81] op_sel_hi:[1,0]
	v_pk_mul_f32 v[64:65], v[64:65], v[80:81] op_sel_hi:[1,0]
	v_cvt_pk_bf16_f32 v72, v72, v73
	v_cvt_pk_bf16_f32 v73, v74, v75
	global_store_dwordx2 v[84:85], v[72:73], off offset:32
	global_store_dwordx4 v[82:83], v[68:71], off offset:512
	v_pk_mul_f32 v[66:67], v[66:67], v[80:81] op_sel_hi:[1,0]
	s_nop 0
	v_cvt_pk_bf16_f32 v68, v68, v69
	v_cvt_pk_bf16_f32 v69, v70, v71
	global_store_dwordx2 v[84:85], v[68:69], off offset:256
	global_store_dwordx4 v[82:83], v[64:67], off offset:576
	s_nop 1
	v_cvt_pk_bf16_f32 v64, v64, v65
	v_cvt_pk_bf16_f32 v65, v66, v67
	global_store_dwordx2 v[84:85], v[64:65], off offset:288
	s_nop 1
	v_add_u32_e32 v66, 0x80, v138
	v_ashrrev_i32_e32 v67, 31, v66
	v_lshlrev_b64 v[68:69], 11, v[66:67]
	v_lshlrev_b64 v[66:67], 10, v[66:67]
	v_lshl_add_u64 v[68:69], s[36:37], 0, v[68:69]
	v_lshl_add_u64 v[68:69], v[68:69], 0, v[132:133]
	v_lshl_add_u64 v[66:67], s[30:31], 0, v[66:67]
	v_lshl_add_u64 v[66:67], v[66:67], 0, v[140:141]
	v_mov_b32_e32 v64, v230
	v_pk_mul_f32 v[62:63], v[62:63], v[64:65] op_sel_hi:[1,0]
	v_pk_mul_f32 v[60:61], v[60:61], v[64:65] op_sel_hi:[1,0]
	v_pk_mul_f32 v[56:57], v[56:57], v[64:65] op_sel_hi:[1,0]
	global_store_dwordx4 v[68:69], v[60:63], off
	v_pk_mul_f32 v[58:59], v[58:59], v[64:65] op_sel_hi:[1,0]
	v_pk_mul_f32 v[52:53], v[52:53], v[64:65] op_sel_hi:[1,0]
	v_cvt_pk_bf16_f32 v60, v60, v61
	v_cvt_pk_bf16_f32 v61, v62, v63
	global_store_dwordx2 v[66:67], v[60:61], off
	global_store_dwordx4 v[68:69], v[56:59], off offset:64
	v_pk_mul_f32 v[54:55], v[54:55], v[64:65] op_sel_hi:[1,0]
	v_pk_mul_f32 v[48:49], v[48:49], v[64:65] op_sel_hi:[1,0]
	v_cvt_pk_bf16_f32 v56, v56, v57
	v_cvt_pk_bf16_f32 v57, v58, v59
	global_store_dwordx2 v[66:67], v[56:57], off offset:32
	global_store_dwordx4 v[68:69], v[52:55], off offset:512
	v_pk_mul_f32 v[50:51], v[50:51], v[64:65] op_sel_hi:[1,0]
	s_nop 0
	v_cvt_pk_bf16_f32 v52, v52, v53
	v_cvt_pk_bf16_f32 v53, v54, v55
	global_store_dwordx2 v[66:67], v[52:53], off offset:256
	global_store_dwordx4 v[68:69], v[48:51], off offset:576
	s_nop 1
	v_cvt_pk_bf16_f32 v48, v48, v49
	v_cvt_pk_bf16_f32 v49, v50, v51
	global_store_dwordx2 v[66:67], v[48:49], off offset:288
	s_nop 1
	v_add_u32_e32 v50, 0x90, v138
	v_ashrrev_i32_e32 v51, 31, v50
	v_lshlrev_b64 v[52:53], 11, v[50:51]
	v_lshlrev_b64 v[50:51], 10, v[50:51]
	v_lshl_add_u64 v[52:53], s[36:37], 0, v[52:53]
	v_lshl_add_u64 v[52:53], v[52:53], 0, v[132:133]
	v_lshl_add_u64 v[50:51], s[30:31], 0, v[50:51]
	v_lshl_add_u64 v[50:51], v[50:51], 0, v[140:141]
	v_mov_b32_e32 v48, v231
	v_pk_mul_f32 v[46:47], v[46:47], v[48:49] op_sel_hi:[1,0]
	v_pk_mul_f32 v[44:45], v[44:45], v[48:49] op_sel_hi:[1,0]
	v_pk_mul_f32 v[40:41], v[40:41], v[48:49] op_sel_hi:[1,0]
	global_store_dwordx4 v[52:53], v[44:47], off
	v_pk_mul_f32 v[42:43], v[42:43], v[48:49] op_sel_hi:[1,0]
	v_pk_mul_f32 v[36:37], v[36:37], v[48:49] op_sel_hi:[1,0]
	v_cvt_pk_bf16_f32 v44, v44, v45
	v_cvt_pk_bf16_f32 v45, v46, v47
	global_store_dwordx2 v[50:51], v[44:45], off
	global_store_dwordx4 v[52:53], v[40:43], off offset:64
	v_pk_mul_f32 v[38:39], v[38:39], v[48:49] op_sel_hi:[1,0]
	v_pk_mul_f32 v[32:33], v[32:33], v[48:49] op_sel_hi:[1,0]
	v_cvt_pk_bf16_f32 v40, v40, v41
	v_cvt_pk_bf16_f32 v41, v42, v43
	global_store_dwordx2 v[50:51], v[40:41], off offset:32
	global_store_dwordx4 v[52:53], v[36:39], off offset:512
	v_pk_mul_f32 v[34:35], v[34:35], v[48:49] op_sel_hi:[1,0]
	s_nop 0
	v_cvt_pk_bf16_f32 v36, v36, v37
	v_cvt_pk_bf16_f32 v37, v38, v39
	global_store_dwordx2 v[50:51], v[36:37], off offset:256
	global_store_dwordx4 v[52:53], v[32:35], off offset:576
	s_nop 1
	v_cvt_pk_bf16_f32 v32, v32, v33
	v_cvt_pk_bf16_f32 v33, v34, v35
	global_store_dwordx2 v[50:51], v[32:33], off offset:288
	s_nop 1
	v_add_u32_e32 v34, 0xa0, v138
	v_ashrrev_i32_e32 v35, 31, v34
	v_lshlrev_b64 v[36:37], 11, v[34:35]
	v_lshlrev_b64 v[34:35], 10, v[34:35]
	v_lshl_add_u64 v[36:37], s[36:37], 0, v[36:37]
	v_lshl_add_u64 v[36:37], v[36:37], 0, v[132:133]
	v_lshl_add_u64 v[34:35], s[30:31], 0, v[34:35]
	v_lshl_add_u64 v[34:35], v[34:35], 0, v[140:141]
	v_mov_b32_e32 v32, v232
	v_pk_mul_f32 v[30:31], v[30:31], v[32:33] op_sel_hi:[1,0]
	v_pk_mul_f32 v[28:29], v[28:29], v[32:33] op_sel_hi:[1,0]
	v_pk_mul_f32 v[24:25], v[24:25], v[32:33] op_sel_hi:[1,0]
	global_store_dwordx4 v[36:37], v[28:31], off
	v_pk_mul_f32 v[26:27], v[26:27], v[32:33] op_sel_hi:[1,0]
	v_pk_mul_f32 v[20:21], v[20:21], v[32:33] op_sel_hi:[1,0]
	v_cvt_pk_bf16_f32 v28, v28, v29
	v_cvt_pk_bf16_f32 v29, v30, v31
	global_store_dwordx2 v[34:35], v[28:29], off
	global_store_dwordx4 v[36:37], v[24:27], off offset:64
	v_pk_mul_f32 v[22:23], v[22:23], v[32:33] op_sel_hi:[1,0]
	v_pk_mul_f32 v[16:17], v[16:17], v[32:33] op_sel_hi:[1,0]
	v_cvt_pk_bf16_f32 v24, v24, v25
	v_cvt_pk_bf16_f32 v25, v26, v27
	global_store_dwordx2 v[34:35], v[24:25], off offset:32
	global_store_dwordx4 v[36:37], v[20:23], off offset:512
	v_pk_mul_f32 v[18:19], v[18:19], v[32:33] op_sel_hi:[1,0]
	s_nop 0
	v_cvt_pk_bf16_f32 v20, v20, v21
	v_cvt_pk_bf16_f32 v21, v22, v23
	global_store_dwordx2 v[34:35], v[20:21], off offset:256
	global_store_dwordx4 v[36:37], v[16:19], off offset:576
	s_nop 1
	v_cvt_pk_bf16_f32 v16, v16, v17
	v_cvt_pk_bf16_f32 v17, v18, v19
	global_store_dwordx2 v[34:35], v[16:17], off offset:288
	s_nop 1
	v_add_u32_e32 v18, 0xb0, v138
	v_ashrrev_i32_e32 v19, 31, v18
	v_lshlrev_b64 v[20:21], 11, v[18:19]
	v_lshlrev_b64 v[18:19], 10, v[18:19]
	v_lshl_add_u64 v[20:21], s[36:37], 0, v[20:21]
	v_lshl_add_u64 v[20:21], v[20:21], 0, v[132:133]
	v_lshl_add_u64 v[18:19], s[30:31], 0, v[18:19]
	v_lshl_add_u64 v[18:19], v[18:19], 0, v[140:141]
	v_mov_b32_e32 v16, v233
	v_pk_mul_f32 v[14:15], v[14:15], v[16:17] op_sel_hi:[1,0]
	v_pk_mul_f32 v[12:13], v[12:13], v[16:17] op_sel_hi:[1,0]
	v_pk_mul_f32 v[8:9], v[8:9], v[16:17] op_sel_hi:[1,0]
	global_store_dwordx4 v[20:21], v[12:15], off
	v_pk_mul_f32 v[10:11], v[10:11], v[16:17] op_sel_hi:[1,0]
	v_pk_mul_f32 v[4:5], v[4:5], v[16:17] op_sel_hi:[1,0]
	v_cvt_pk_bf16_f32 v12, v12, v13
	v_cvt_pk_bf16_f32 v13, v14, v15
	global_store_dwordx2 v[18:19], v[12:13], off
	global_store_dwordx4 v[20:21], v[8:11], off offset:64
	v_pk_mul_f32 v[6:7], v[6:7], v[16:17] op_sel_hi:[1,0]
	v_pk_mul_f32 v[0:1], v[0:1], v[16:17] op_sel_hi:[1,0]
	v_cvt_pk_bf16_f32 v8, v8, v9
	v_cvt_pk_bf16_f32 v9, v10, v11
	global_store_dwordx2 v[18:19], v[8:9], off offset:32
	global_store_dwordx4 v[20:21], v[4:7], off offset:512
	v_pk_mul_f32 v[2:3], v[2:3], v[16:17] op_sel_hi:[1,0]
	s_nop 0
	v_cvt_pk_bf16_f32 v4, v4, v5
	v_cvt_pk_bf16_f32 v5, v6, v7
	global_store_dwordx2 v[18:19], v[4:5], off offset:256
	global_store_dwordx4 v[20:21], v[0:3], off offset:576
	s_nop 1
	v_cvt_pk_bf16_f32 v0, v0, v1
	v_cvt_pk_bf16_f32 v1, v2, v3
	global_store_dwordx2 v[18:19], v[0:1], off offset:288
	s_cbranch_vccnz .LBB0_318
	s_andn2_b64 vcc, exec, s[4:5]
	s_cbranch_vccnz .LBB0_317
	s_barrier
	s_branch .LBB0_317

.LBB0_1315:
	v_lshl_add_u32 v144, s36, 8, v148
	v_ashrrev_i32_e32 v145, 31, v144
	v_lshl_add_u64 v[146:147], v[144:145], 2, s[18:19]
	s_waitcnt lgkmcnt(0)
	global_load_dword v226, v[146:147], off
	global_load_dword v227, v[146:147], off offset:64
	global_load_dword v228, v[146:147], off offset:128
	global_load_dword v229, v[146:147], off offset:192
	global_load_dword v230, v[146:147], off offset:512
	global_load_dword v231, v[146:147], off offset:576
	global_load_dword v232, v[146:147], off offset:640
	global_load_dword v233, v[146:147], off offset:704
	v_lshl_or_b32 v158, s59, 7, v150
	v_mov_b32_e32 v163, v114
	v_mov_b32_e32 v114, v119
	v_mov_b32_e32 v160, v124
	v_mov_b32_e32 v161, v120
	v_mov_b32_e32 v120, v125
	v_mov_b32_e32 v124, v126
	v_mov_b32_e32 v125, v122
	v_mov_b32_e32 v122, v127
	v_mov_b32_e32 v126, v116
	v_mov_b32_e32 v127, v112
	v_mov_b32_e32 v112, v117
	v_mov_b32_e32 v162, v118
	v_mov_b64_e32 v[116:117], s[16:17]
	v_ashrrev_i32_e32 v159, 31, v158
	v_or_b32_e32 v166, 16, v144
	v_mad_i64_i32 v[164:165], s[38:39], v144, s58, v[116:117]
	v_lshlrev_b64 v[118:119], 1, v[158:159]
	v_ashrrev_i32_e32 v167, 31, v166
	v_lshl_add_u64 v[158:159], v[164:165], 0, v[118:119]
	v_lshl_add_u64 v[164:165], v[166:167], 2, s[18:19]
	s_andn2_b64 vcc, exec, s[4:5]
	s_mov_b64 s[4:5], -1
	s_waitcnt vmcnt(0)
	v_mov_b32_e32 v154, v226
	v_pk_mul_f32 v[114:115], v[114:115], v[154:155] op_sel_hi:[1,0]
	v_pk_mul_f32 v[160:161], v[160:161], v[154:155] op_sel_hi:[1,0]
	v_pk_mul_f32 v[120:121], v[120:121], v[154:155] op_sel_hi:[1,0]
	v_pk_mul_f32 v[124:125], v[124:125], v[154:155] op_sel_hi:[1,0]
	v_pk_mul_f32 v[122:123], v[122:123], v[154:155] op_sel_hi:[1,0]
	v_pk_mul_f32 v[126:127], v[126:127], v[154:155] op_sel_hi:[1,0]
	v_pk_mul_f32 v[112:113], v[112:113], v[154:155] op_sel_hi:[1,0]
	v_pk_mul_f32 v[162:163], v[162:163], v[154:155] op_sel_hi:[1,0]
	v_mul_f32_e32 v170, 0xbfb8aa3b, v115
	v_mul_f32_e32 v145, 0xbfb8aa3b, v161
	v_mul_f32_e32 v154, 0xbfb8aa3b, v121
	v_mul_f32_e32 v155, 0xbfb8aa3b, v125
	v_mul_f32_e32 v157, 0xbfb8aa3b, v123
	v_mul_f32_e32 v167, 0xbfb8aa3b, v127
	v_mul_f32_e32 v168, 0xbfb8aa3b, v113
	v_mul_f32_e32 v169, 0xbfb8aa3b, v163
	v_exp_f32_e32 v170, v170
	v_exp_f32_e32 v145, v145
	v_exp_f32_e32 v154, v154
	v_exp_f32_e32 v155, v155
	v_exp_f32_e32 v157, v157
	v_exp_f32_e32 v167, v167
	v_exp_f32_e32 v168, v168
	v_exp_f32_e32 v169, v169
	v_add_f32_e32 v170, 1.0, v170
	v_add_f32_e32 v145, 1.0, v145
	v_add_f32_e32 v154, 1.0, v154
	v_add_f32_e32 v155, 1.0, v155
	v_add_f32_e32 v157, 1.0, v157
	v_add_f32_e32 v167, 1.0, v167
	v_add_f32_e32 v168, 1.0, v168
	v_add_f32_e32 v169, 1.0, v169
	v_rcp_f32_e32 v170, v170
	v_rcp_f32_e32 v145, v145
	v_rcp_f32_e32 v154, v154
	v_rcp_f32_e32 v155, v155
	v_rcp_f32_e32 v157, v157
	v_rcp_f32_e32 v167, v167
	v_rcp_f32_e32 v168, v168
	v_rcp_f32_e32 v169, v169
	v_mul_f32_e32 v115, v115, v170
	v_mul_f32_e32 v145, v161, v145
	v_mul_f32_e32 v121, v121, v154
	v_mul_f32_e32 v125, v125, v155
	v_mul_f32_e32 v123, v123, v157
	v_mul_f32_e32 v127, v127, v167
	v_mul_f32_e32 v113, v113, v168
	v_mul_f32_e32 v154, v163, v169
	v_mul_f32_e32 v115, v114, v115
	v_mul_f32_e32 v145, v160, v145
	v_mul_f32_e32 v120, v120, v121
	v_mul_f32_e32 v121, v124, v125
	v_mul_f32_e32 v122, v122, v123
	v_mul_f32_e32 v123, v126, v127
	v_mul_f32_e32 v124, v112, v113
	v_mul_f32_e32 v125, v162, v154
	v_cvt_pk_bf16_f32 v112, v145, v120
	v_cvt_pk_bf16_f32 v113, v121, v122
	v_cvt_pk_bf16_f32 v114, v123, v124
	v_cvt_pk_bf16_f32 v115, v125, v115
	global_store_dwordx4 v[158:159], v[112:115], off
	s_nop 1
	v_mad_i64_i32 v[120:121], s[38:39], v166, s58, v[116:117]
	v_mov_b32_e32 v115, v104
	v_mov_b32_e32 v104, v109
	v_mov_b32_e32 v109, v106
	v_mov_b32_e32 v106, v111
	v_mov_b32_e32 v111, v96
	v_mov_b32_e32 v96, v101
	v_mov_b32_e32 v101, v98
	v_mov_b32_e32 v98, v103
	v_mov_b32_e32 v114, v108
	v_mov_b32_e32 v108, v110
	v_mov_b32_e32 v110, v100
	v_mov_b32_e32 v100, v102
	v_or_b32_e32 v102, 32, v144
	v_ashrrev_i32_e32 v103, 31, v102
	v_lshl_add_u64 v[122:123], v[102:103], 2, s[18:19]
	v_lshl_add_u64 v[120:121], v[120:121], 0, v[118:119]
	v_mov_b32_e32 v112, v227
	v_pk_mul_f32 v[98:99], v[98:99], v[112:113] op_sel_hi:[1,0]
	v_pk_mul_f32 v[114:115], v[114:115], v[112:113] op_sel_hi:[1,0]
	v_pk_mul_f32 v[104:105], v[104:105], v[112:113] op_sel_hi:[1,0]
	v_pk_mul_f32 v[108:109], v[108:109], v[112:113] op_sel_hi:[1,0]
	v_pk_mul_f32 v[106:107], v[106:107], v[112:113] op_sel_hi:[1,0]
	v_pk_mul_f32 v[110:111], v[110:111], v[112:113] op_sel_hi:[1,0]
	v_pk_mul_f32 v[96:97], v[96:97], v[112:113] op_sel_hi:[1,0]
	v_pk_mul_f32 v[100:101], v[100:101], v[112:113] op_sel_hi:[1,0]
	v_mul_f32_e32 v145, 0xbfb8aa3b, v99
	v_mul_f32_e32 v103, 0xbfb8aa3b, v115
	v_mul_f32_e32 v112, 0xbfb8aa3b, v105
	v_mul_f32_e32 v113, 0xbfb8aa3b, v109
	v_mul_f32_e32 v124, 0xbfb8aa3b, v107
	v_mul_f32_e32 v125, 0xbfb8aa3b, v111
	v_mul_f32_e32 v126, 0xbfb8aa3b, v97
	v_mul_f32_e32 v127, 0xbfb8aa3b, v101
	v_exp_f32_e32 v145, v145
	v_exp_f32_e32 v103, v103
	v_exp_f32_e32 v112, v112
	v_exp_f32_e32 v113, v113
	v_exp_f32_e32 v124, v124
	v_exp_f32_e32 v125, v125
	v_exp_f32_e32 v126, v126
	v_exp_f32_e32 v127, v127
	v_add_f32_e32 v145, 1.0, v145
	v_add_f32_e32 v103, 1.0, v103
	v_add_f32_e32 v112, 1.0, v112
	v_add_f32_e32 v113, 1.0, v113
	v_add_f32_e32 v124, 1.0, v124
	v_add_f32_e32 v125, 1.0, v125
	v_add_f32_e32 v126, 1.0, v126
	v_add_f32_e32 v127, 1.0, v127
	v_rcp_f32_e32 v145, v145
	v_rcp_f32_e32 v103, v103
	v_rcp_f32_e32 v112, v112
	v_rcp_f32_e32 v113, v113
	v_rcp_f32_e32 v124, v124
	v_rcp_f32_e32 v125, v125
	v_rcp_f32_e32 v126, v126
	v_rcp_f32_e32 v127, v127
	v_mul_f32_e32 v99, v99, v145
	v_mul_f32_e32 v103, v115, v103
	v_mul_f32_e32 v105, v105, v112
	v_mul_f32_e32 v109, v109, v113
	v_mul_f32_e32 v107, v107, v124
	v_mul_f32_e32 v111, v111, v125
	v_mul_f32_e32 v97, v97, v126
	v_mul_f32_e32 v101, v101, v127
	v_mul_f32_e32 v99, v98, v99
	v_mul_f32_e32 v103, v114, v103
	v_mul_f32_e32 v104, v104, v105
	v_mul_f32_e32 v105, v108, v109
	v_mul_f32_e32 v106, v106, v107
	v_mul_f32_e32 v107, v110, v111
	v_mul_f32_e32 v108, v96, v97
	v_mul_f32_e32 v100, v100, v101
	v_cvt_pk_bf16_f32 v96, v103, v104
	v_cvt_pk_bf16_f32 v97, v105, v106
	v_cvt_pk_bf16_f32 v98, v107, v108
	v_cvt_pk_bf16_f32 v99, v100, v99
	global_store_dwordx4 v[120:121], v[96:99], off
	s_nop 1
	v_mad_i64_i32 v[100:101], s[38:39], v102, s58, v[116:117]
	v_mov_b32_e32 v99, v88
	v_mov_b32_e32 v88, v93
	v_mov_b32_e32 v93, v90
	v_mov_b32_e32 v90, v95
	v_mov_b32_e32 v95, v80
	v_mov_b32_e32 v80, v85
	v_mov_b32_e32 v85, v82
	v_mov_b32_e32 v82, v87
	v_mov_b32_e32 v98, v92
	v_mov_b32_e32 v92, v94
	v_mov_b32_e32 v94, v84
	v_mov_b32_e32 v84, v86
	v_or_b32_e32 v86, 48, v144
	v_ashrrev_i32_e32 v87, 31, v86
	v_lshl_add_u64 v[102:103], v[86:87], 2, s[18:19]
	v_lshl_add_u64 v[100:101], v[100:101], 0, v[118:119]
	v_mov_b32_e32 v96, v228
	v_pk_mul_f32 v[82:83], v[82:83], v[96:97] op_sel_hi:[1,0]
	v_pk_mul_f32 v[98:99], v[98:99], v[96:97] op_sel_hi:[1,0]
	v_pk_mul_f32 v[88:89], v[88:89], v[96:97] op_sel_hi:[1,0]
	v_pk_mul_f32 v[92:93], v[92:93], v[96:97] op_sel_hi:[1,0]
	v_pk_mul_f32 v[90:91], v[90:91], v[96:97] op_sel_hi:[1,0]
	v_pk_mul_f32 v[94:95], v[94:95], v[96:97] op_sel_hi:[1,0]
	v_pk_mul_f32 v[80:81], v[80:81], v[96:97] op_sel_hi:[1,0]
	v_pk_mul_f32 v[84:85], v[84:85], v[96:97] op_sel_hi:[1,0]
	v_mul_f32_e32 v108, 0xbfb8aa3b, v83
	v_mul_f32_e32 v87, 0xbfb8aa3b, v99
	v_mul_f32_e32 v96, 0xbfb8aa3b, v89
	v_mul_f32_e32 v97, 0xbfb8aa3b, v93
	v_mul_f32_e32 v104, 0xbfb8aa3b, v91
	v_mul_f32_e32 v105, 0xbfb8aa3b, v95
	v_mul_f32_e32 v106, 0xbfb8aa3b, v81
	v_mul_f32_e32 v107, 0xbfb8aa3b, v85
	v_exp_f32_e32 v108, v108
	v_exp_f32_e32 v87, v87
	v_exp_f32_e32 v96, v96
	v_exp_f32_e32 v97, v97
	v_exp_f32_e32 v104, v104
	v_exp_f32_e32 v105, v105
	v_exp_f32_e32 v106, v106
	v_exp_f32_e32 v107, v107
	v_add_f32_e32 v108, 1.0, v108
	v_add_f32_e32 v87, 1.0, v87
	v_add_f32_e32 v96, 1.0, v96
	v_add_f32_e32 v97, 1.0, v97
	v_add_f32_e32 v104, 1.0, v104
	v_add_f32_e32 v105, 1.0, v105
	v_add_f32_e32 v106, 1.0, v106
	v_add_f32_e32 v107, 1.0, v107
	v_rcp_f32_e32 v108, v108
	v_rcp_f32_e32 v87, v87
	v_rcp_f32_e32 v96, v96
	v_rcp_f32_e32 v97, v97
	v_rcp_f32_e32 v104, v104
	v_rcp_f32_e32 v105, v105
	v_rcp_f32_e32 v106, v106
	v_rcp_f32_e32 v107, v107
	v_mul_f32_e32 v83, v83, v108
	v_mul_f32_e32 v87, v99, v87
	v_mul_f32_e32 v89, v89, v96
	v_mul_f32_e32 v93, v93, v97
	v_mul_f32_e32 v91, v91, v104
	v_mul_f32_e32 v95, v95, v105
	v_mul_f32_e32 v81, v81, v106
	v_mul_f32_e32 v85, v85, v107
	v_mul_f32_e32 v83, v82, v83
	v_mul_f32_e32 v87, v98, v87
	v_mul_f32_e32 v88, v88, v89
	v_mul_f32_e32 v89, v92, v93
	v_mul_f32_e32 v90, v90, v91
	v_mul_f32_e32 v91, v94, v95
	v_mul_f32_e32 v92, v80, v81
	v_mul_f32_e32 v84, v84, v85
	v_cvt_pk_bf16_f32 v80, v87, v88
	v_cvt_pk_bf16_f32 v81, v89, v90
	v_cvt_pk_bf16_f32 v82, v91, v92
	v_cvt_pk_bf16_f32 v83, v84, v83
	global_store_dwordx4 v[100:101], v[80:83], off
	s_nop 1
	s_nop 0
	v_mov_b32_e32 v82, v76
	v_mov_b32_e32 v83, v72
	v_mov_b32_e32 v72, v77
	v_mov_b32_e32 v76, v78
	v_mov_b32_e32 v77, v74
	v_mov_b32_e32 v74, v79
	v_mov_b32_e32 v78, v64
	v_mov_b32_e32 v79, v68
	v_mov_b32_e32 v68, v65
	v_mov_b32_e32 v64, v66
	v_mov_b32_e32 v65, v70
	v_mov_b32_e32 v70, v67
	v_mad_i64_i32 v[66:67], s[38:39], v86, s58, v[116:117]
	v_lshl_add_u64 v[84:85], v[66:67], 0, v[118:119]
	v_mov_b32_e32 v80, v229
	v_pk_mul_f32 v[66:67], v[82:83], v[80:81] op_sel_hi:[1,0]
	v_pk_mul_f32 v[72:73], v[72:73], v[80:81] op_sel_hi:[1,0]
	v_pk_mul_f32 v[76:77], v[76:77], v[80:81] op_sel_hi:[1,0]
	v_pk_mul_f32 v[74:75], v[74:75], v[80:81] op_sel_hi:[1,0]
	v_pk_mul_f32 v[78:79], v[78:79], v[80:81] op_sel_hi:[1,0]
	v_pk_mul_f32 v[68:69], v[68:69], v[80:81] op_sel_hi:[1,0]
	v_pk_mul_f32 v[64:65], v[64:65], v[80:81] op_sel_hi:[1,0]
	v_pk_mul_f32 v[70:71], v[70:71], v[80:81] op_sel_hi:[1,0]
	v_mul_f32_e32 v80, 0xbfb8aa3b, v67
	v_mul_f32_e32 v81, 0xbfb8aa3b, v73
	v_mul_f32_e32 v82, 0xbfb8aa3b, v77
	v_mul_f32_e32 v83, 0xbfb8aa3b, v75
	v_mul_f32_e32 v86, 0xbfb8aa3b, v79
	v_mul_f32_e32 v87, 0xbfb8aa3b, v69
	v_mul_f32_e32 v88, 0xbfb8aa3b, v65
	v_mul_f32_e32 v89, 0xbfb8aa3b, v71
	v_exp_f32_e32 v80, v80
	v_exp_f32_e32 v81, v81
	v_exp_f32_e32 v82, v82
	v_exp_f32_e32 v83, v83
	v_exp_f32_e32 v86, v86
	v_exp_f32_e32 v87, v87
	v_exp_f32_e32 v88, v88
	v_exp_f32_e32 v89, v89
	v_add_f32_e32 v80, 1.0, v80
	v_add_f32_e32 v81, 1.0, v81
	v_add_f32_e32 v82, 1.0, v82
	v_add_f32_e32 v83, 1.0, v83
	v_add_f32_e32 v86, 1.0, v86
	v_add_f32_e32 v87, 1.0, v87
	v_add_f32_e32 v88, 1.0, v88
	v_add_f32_e32 v89, 1.0, v89
	v_rcp_f32_e32 v80, v80
	v_rcp_f32_e32 v81, v81
	v_rcp_f32_e32 v82, v82
	v_rcp_f32_e32 v83, v83
	v_rcp_f32_e32 v86, v86
	v_rcp_f32_e32 v87, v87
	v_rcp_f32_e32 v88, v88
	v_rcp_f32_e32 v89, v89
	v_mul_f32_e32 v67, v67, v80
	v_mul_f32_e32 v73, v73, v81
	v_mul_f32_e32 v77, v77, v82
	v_mul_f32_e32 v75, v75, v83
	v_mul_f32_e32 v79, v79, v86
	v_mul_f32_e32 v69, v69, v87
	v_mul_f32_e32 v65, v65, v88
	v_mul_f32_e32 v71, v71, v89
	v_mul_f32_e32 v66, v66, v67
	v_mul_f32_e32 v67, v72, v73
	v_mul_f32_e32 v72, v76, v77
	v_mul_f32_e32 v73, v74, v75
	v_mul_f32_e32 v74, v78, v79
	v_mul_f32_e32 v68, v68, v69
	v_mul_f32_e32 v69, v64, v65
	v_mul_f32_e32 v70, v70, v71
	v_cvt_pk_bf16_f32 v64, v66, v67
	v_cvt_pk_bf16_f32 v65, v72, v73
	v_cvt_pk_bf16_f32 v66, v74, v68
	v_cvt_pk_bf16_f32 v67, v69, v70
	global_store_dwordx4 v[84:85], v[64:67], off
	s_nop 1
	s_nop 0
	v_mov_b32_e32 v66, v60
	v_mov_b32_e32 v60, v62
	v_mov_b32_e32 v62, v48
	v_mov_b32_e32 v48, v50
	v_add_u32_e32 v50, 0x80, v144
	v_mov_b32_e32 v67, v56
	v_mov_b32_e32 v56, v61
	v_mov_b32_e32 v61, v58
	v_mov_b32_e32 v58, v63
	v_mov_b32_e32 v63, v52
	v_mov_b32_e32 v52, v49
	v_mov_b32_e32 v49, v54
	v_mov_b32_e32 v54, v51
	v_mad_i64_i32 v[50:51], s[38:39], v50, s58, v[116:117]
	v_lshl_add_u64 v[68:69], v[50:51], 0, v[118:119]
	v_mov_b32_e32 v64, v230
	v_pk_mul_f32 v[50:51], v[66:67], v[64:65] op_sel_hi:[1,0]
	v_pk_mul_f32 v[56:57], v[56:57], v[64:65] op_sel_hi:[1,0]
	v_pk_mul_f32 v[60:61], v[60:61], v[64:65] op_sel_hi:[1,0]
	v_pk_mul_f32 v[58:59], v[58:59], v[64:65] op_sel_hi:[1,0]
	v_pk_mul_f32 v[62:63], v[62:63], v[64:65] op_sel_hi:[1,0]
	v_pk_mul_f32 v[52:53], v[52:53], v[64:65] op_sel_hi:[1,0]
	v_pk_mul_f32 v[48:49], v[48:49], v[64:65] op_sel_hi:[1,0]
	v_pk_mul_f32 v[54:55], v[54:55], v[64:65] op_sel_hi:[1,0]
	v_mul_f32_e32 v64, 0xbfb8aa3b, v51
	v_mul_f32_e32 v65, 0xbfb8aa3b, v57
	v_mul_f32_e32 v66, 0xbfb8aa3b, v61
	v_mul_f32_e32 v67, 0xbfb8aa3b, v59
	v_mul_f32_e32 v70, 0xbfb8aa3b, v63
	v_mul_f32_e32 v71, 0xbfb8aa3b, v53
	v_mul_f32_e32 v72, 0xbfb8aa3b, v49
	v_mul_f32_e32 v73, 0xbfb8aa3b, v55
	v_exp_f32_e32 v64, v64
	v_exp_f32_e32 v65, v65
	v_exp_f32_e32 v66, v66
	v_exp_f32_e32 v67, v67
	v_exp_f32_e32 v70, v70
	v_exp_f32_e32 v71, v71
	v_exp_f32_e32 v72, v72
	v_exp_f32_e32 v73, v73
	v_add_f32_e32 v64, 1.0, v64
	v_add_f32_e32 v65, 1.0, v65
	v_add_f32_e32 v66, 1.0, v66
	v_add_f32_e32 v67, 1.0, v67
	v_add_f32_e32 v70, 1.0, v70
	v_add_f32_e32 v71, 1.0, v71
	v_add_f32_e32 v72, 1.0, v72
	v_add_f32_e32 v73, 1.0, v73
	v_rcp_f32_e32 v64, v64
	v_rcp_f32_e32 v65, v65
	v_rcp_f32_e32 v66, v66
	v_rcp_f32_e32 v67, v67
	v_rcp_f32_e32 v70, v70
	v_rcp_f32_e32 v71, v71
	v_rcp_f32_e32 v72, v72
	v_rcp_f32_e32 v73, v73
	v_mul_f32_e32 v51, v51, v64
	v_mul_f32_e32 v57, v57, v65
	v_mul_f32_e32 v61, v61, v66
	v_mul_f32_e32 v59, v59, v67
	v_mul_f32_e32 v63, v63, v70
	v_mul_f32_e32 v53, v53, v71
	v_mul_f32_e32 v49, v49, v72
	v_mul_f32_e32 v55, v55, v73
	v_mul_f32_e32 v50, v50, v51
	v_mul_f32_e32 v51, v56, v57
	v_mul_f32_e32 v56, v60, v61
	v_mul_f32_e32 v57, v58, v59
	v_mul_f32_e32 v58, v62, v63
	v_mul_f32_e32 v52, v52, v53
	v_mul_f32_e32 v53, v48, v49
	v_mul_f32_e32 v54, v54, v55
	v_cvt_pk_bf16_f32 v48, v50, v51
	v_cvt_pk_bf16_f32 v49, v56, v57
	v_cvt_pk_bf16_f32 v50, v58, v52
	v_cvt_pk_bf16_f32 v51, v53, v54
	global_store_dwordx4 v[68:69], v[48:51], off
	s_nop 1
	s_nop 0
	v_mov_b32_e32 v50, v44
	v_mov_b32_e32 v44, v46
	v_mov_b32_e32 v46, v32
	v_mov_b32_e32 v32, v34
	v_add_u32_e32 v34, 0x90, v144
	v_mov_b32_e32 v51, v40
	v_mov_b32_e32 v40, v45
	v_mov_b32_e32 v45, v42
	v_mov_b32_e32 v42, v47
	v_mov_b32_e32 v47, v36
	v_mov_b32_e32 v36, v33
	v_mov_b32_e32 v33, v38
	v_mov_b32_e32 v38, v35
	v_mad_i64_i32 v[34:35], s[38:39], v34, s58, v[116:117]
	v_lshl_add_u64 v[52:53], v[34:35], 0, v[118:119]
	v_mov_b32_e32 v48, v231
	v_pk_mul_f32 v[34:35], v[50:51], v[48:49] op_sel_hi:[1,0]
	v_pk_mul_f32 v[40:41], v[40:41], v[48:49] op_sel_hi:[1,0]
	v_pk_mul_f32 v[44:45], v[44:45], v[48:49] op_sel_hi:[1,0]
	v_pk_mul_f32 v[42:43], v[42:43], v[48:49] op_sel_hi:[1,0]
	v_pk_mul_f32 v[46:47], v[46:47], v[48:49] op_sel_hi:[1,0]
	v_pk_mul_f32 v[36:37], v[36:37], v[48:49] op_sel_hi:[1,0]
	v_pk_mul_f32 v[32:33], v[32:33], v[48:49] op_sel_hi:[1,0]
	v_pk_mul_f32 v[38:39], v[38:39], v[48:49] op_sel_hi:[1,0]
	v_mul_f32_e32 v48, 0xbfb8aa3b, v35
	v_mul_f32_e32 v49, 0xbfb8aa3b, v41
	v_mul_f32_e32 v50, 0xbfb8aa3b, v45
	v_mul_f32_e32 v51, 0xbfb8aa3b, v43
	v_mul_f32_e32 v54, 0xbfb8aa3b, v47
	v_mul_f32_e32 v55, 0xbfb8aa3b, v37
	v_mul_f32_e32 v56, 0xbfb8aa3b, v33
	v_mul_f32_e32 v57, 0xbfb8aa3b, v39
	v_exp_f32_e32 v48, v48
	v_exp_f32_e32 v49, v49
	v_exp_f32_e32 v50, v50
	v_exp_f32_e32 v51, v51
	v_exp_f32_e32 v54, v54
	v_exp_f32_e32 v55, v55
	v_exp_f32_e32 v56, v56
	v_exp_f32_e32 v57, v57
	v_add_f32_e32 v48, 1.0, v48
	v_add_f32_e32 v49, 1.0, v49
	v_add_f32_e32 v50, 1.0, v50
	v_add_f32_e32 v51, 1.0, v51
	v_add_f32_e32 v54, 1.0, v54
	v_add_f32_e32 v55, 1.0, v55
	v_add_f32_e32 v56, 1.0, v56
	v_add_f32_e32 v57, 1.0, v57
	v_rcp_f32_e32 v48, v48
	v_rcp_f32_e32 v49, v49
	v_rcp_f32_e32 v50, v50
	v_rcp_f32_e32 v51, v51
	v_rcp_f32_e32 v54, v54
	v_rcp_f32_e32 v55, v55
	v_rcp_f32_e32 v56, v56
	v_rcp_f32_e32 v57, v57
	v_mul_f32_e32 v35, v35, v48
	v_mul_f32_e32 v41, v41, v49
	v_mul_f32_e32 v45, v45, v50
	v_mul_f32_e32 v43, v43, v51
	v_mul_f32_e32 v47, v47, v54
	v_mul_f32_e32 v37, v37, v55
	v_mul_f32_e32 v33, v33, v56
	v_mul_f32_e32 v39, v39, v57
	v_mul_f32_e32 v34, v34, v35
	v_mul_f32_e32 v35, v40, v41
	v_mul_f32_e32 v40, v44, v45
	v_mul_f32_e32 v41, v42, v43
	v_mul_f32_e32 v42, v46, v47
	v_mul_f32_e32 v36, v36, v37
	v_mul_f32_e32 v37, v32, v33
	v_mul_f32_e32 v38, v38, v39
	v_cvt_pk_bf16_f32 v32, v34, v35
	v_cvt_pk_bf16_f32 v33, v40, v41
	v_cvt_pk_bf16_f32 v34, v42, v36
	v_cvt_pk_bf16_f32 v35, v37, v38
	global_store_dwordx4 v[52:53], v[32:35], off
	s_nop 1
	s_nop 0
	v_mov_b32_e32 v34, v28
	v_mov_b32_e32 v28, v30
	v_mov_b32_e32 v30, v16
	v_mov_b32_e32 v16, v18
	v_add_u32_e32 v18, 0xa0, v144
	v_mov_b32_e32 v35, v24
	v_mov_b32_e32 v24, v29
	v_mov_b32_e32 v29, v26
	v_mov_b32_e32 v26, v31
	v_mov_b32_e32 v31, v20
	v_mov_b32_e32 v20, v17
	v_mov_b32_e32 v17, v22
	v_mov_b32_e32 v22, v19
	v_mad_i64_i32 v[18:19], s[38:39], v18, s58, v[116:117]
	v_lshl_add_u64 v[36:37], v[18:19], 0, v[118:119]
	v_mov_b32_e32 v32, v232
	v_pk_mul_f32 v[18:19], v[34:35], v[32:33] op_sel_hi:[1,0]
	v_pk_mul_f32 v[24:25], v[24:25], v[32:33] op_sel_hi:[1,0]
	v_pk_mul_f32 v[28:29], v[28:29], v[32:33] op_sel_hi:[1,0]
	v_pk_mul_f32 v[26:27], v[26:27], v[32:33] op_sel_hi:[1,0]
	v_pk_mul_f32 v[30:31], v[30:31], v[32:33] op_sel_hi:[1,0]
	v_pk_mul_f32 v[20:21], v[20:21], v[32:33] op_sel_hi:[1,0]
	v_pk_mul_f32 v[16:17], v[16:17], v[32:33] op_sel_hi:[1,0]
	v_pk_mul_f32 v[22:23], v[22:23], v[32:33] op_sel_hi:[1,0]
	v_mul_f32_e32 v32, 0xbfb8aa3b, v19
	v_mul_f32_e32 v33, 0xbfb8aa3b, v25
	v_mul_f32_e32 v34, 0xbfb8aa3b, v29
	v_mul_f32_e32 v35, 0xbfb8aa3b, v27
	v_mul_f32_e32 v38, 0xbfb8aa3b, v31
	v_mul_f32_e32 v39, 0xbfb8aa3b, v21
	v_mul_f32_e32 v40, 0xbfb8aa3b, v17
	v_mul_f32_e32 v41, 0xbfb8aa3b, v23
	v_exp_f32_e32 v32, v32
	v_exp_f32_e32 v33, v33
	v_exp_f32_e32 v34, v34
	v_exp_f32_e32 v35, v35
	v_exp_f32_e32 v38, v38
	v_exp_f32_e32 v39, v39
	v_exp_f32_e32 v40, v40
	v_exp_f32_e32 v41, v41
	v_add_f32_e32 v32, 1.0, v32
	v_add_f32_e32 v33, 1.0, v33
	v_add_f32_e32 v34, 1.0, v34
	v_add_f32_e32 v35, 1.0, v35
	v_add_f32_e32 v38, 1.0, v38
	v_add_f32_e32 v39, 1.0, v39
	v_add_f32_e32 v40, 1.0, v40
	v_add_f32_e32 v41, 1.0, v41
	v_rcp_f32_e32 v32, v32
	v_rcp_f32_e32 v33, v33
	v_rcp_f32_e32 v34, v34
	v_rcp_f32_e32 v35, v35
	v_rcp_f32_e32 v38, v38
	v_rcp_f32_e32 v39, v39
	v_rcp_f32_e32 v40, v40
	v_rcp_f32_e32 v41, v41
	v_mul_f32_e32 v19, v19, v32
	v_mul_f32_e32 v25, v25, v33
	v_mul_f32_e32 v29, v29, v34
	v_mul_f32_e32 v27, v27, v35
	v_mul_f32_e32 v31, v31, v38
	v_mul_f32_e32 v21, v21, v39
	v_mul_f32_e32 v17, v17, v40
	v_mul_f32_e32 v23, v23, v41
	v_mul_f32_e32 v18, v18, v19
	v_mul_f32_e32 v19, v24, v25
	v_mul_f32_e32 v24, v28, v29
	v_mul_f32_e32 v25, v26, v27
	v_mul_f32_e32 v26, v30, v31
	v_mul_f32_e32 v20, v20, v21
	v_mul_f32_e32 v21, v16, v17
	v_mul_f32_e32 v22, v22, v23
	v_cvt_pk_bf16_f32 v16, v18, v19
	v_cvt_pk_bf16_f32 v17, v24, v25
	v_cvt_pk_bf16_f32 v18, v26, v20
	v_cvt_pk_bf16_f32 v19, v21, v22
	global_store_dwordx4 v[36:37], v[16:19], off
	s_nop 1
	s_nop 0
	v_mov_b32_e32 v18, v12
	v_mov_b32_e32 v12, v14
	v_mov_b32_e32 v14, v0
	v_mov_b32_e32 v0, v2
	v_add_u32_e32 v2, 0xb0, v144
	v_mov_b32_e32 v19, v8
	v_mov_b32_e32 v8, v13
	v_mov_b32_e32 v13, v10
	v_mov_b32_e32 v10, v15
	v_mov_b32_e32 v15, v4
	v_mov_b32_e32 v4, v1
	v_mov_b32_e32 v1, v6
	v_mov_b32_e32 v6, v3
	v_mad_i64_i32 v[2:3], s[38:39], v2, s58, v[116:117]
	v_lshl_add_u64 v[20:21], v[2:3], 0, v[118:119]
	v_mov_b32_e32 v16, v233
	v_pk_mul_f32 v[2:3], v[18:19], v[16:17] op_sel_hi:[1,0]
	v_pk_mul_f32 v[8:9], v[8:9], v[16:17] op_sel_hi:[1,0]
	v_pk_mul_f32 v[12:13], v[12:13], v[16:17] op_sel_hi:[1,0]
	v_pk_mul_f32 v[10:11], v[10:11], v[16:17] op_sel_hi:[1,0]
	v_pk_mul_f32 v[14:15], v[14:15], v[16:17] op_sel_hi:[1,0]
	v_pk_mul_f32 v[4:5], v[4:5], v[16:17] op_sel_hi:[1,0]
	v_pk_mul_f32 v[0:1], v[0:1], v[16:17] op_sel_hi:[1,0]
	v_pk_mul_f32 v[6:7], v[6:7], v[16:17] op_sel_hi:[1,0]
	v_mul_f32_e32 v16, 0xbfb8aa3b, v3
	v_mul_f32_e32 v17, 0xbfb8aa3b, v9
	v_mul_f32_e32 v18, 0xbfb8aa3b, v13
	v_mul_f32_e32 v19, 0xbfb8aa3b, v11
	v_mul_f32_e32 v22, 0xbfb8aa3b, v15
	v_mul_f32_e32 v23, 0xbfb8aa3b, v5
	v_mul_f32_e32 v24, 0xbfb8aa3b, v1
	v_mul_f32_e32 v25, 0xbfb8aa3b, v7
	v_exp_f32_e32 v16, v16
	v_exp_f32_e32 v17, v17
	v_exp_f32_e32 v18, v18
	v_exp_f32_e32 v19, v19
	v_exp_f32_e32 v22, v22
	v_exp_f32_e32 v23, v23
	v_exp_f32_e32 v24, v24
	v_exp_f32_e32 v25, v25
	v_add_f32_e32 v16, 1.0, v16
	v_add_f32_e32 v17, 1.0, v17
	v_add_f32_e32 v18, 1.0, v18
	v_add_f32_e32 v19, 1.0, v19
	v_add_f32_e32 v22, 1.0, v22
	v_add_f32_e32 v23, 1.0, v23
	v_add_f32_e32 v24, 1.0, v24
	v_add_f32_e32 v25, 1.0, v25
	v_rcp_f32_e32 v16, v16
	v_rcp_f32_e32 v17, v17
	v_rcp_f32_e32 v18, v18
	v_rcp_f32_e32 v19, v19
	v_rcp_f32_e32 v22, v22
	v_rcp_f32_e32 v23, v23
	v_rcp_f32_e32 v24, v24
	v_rcp_f32_e32 v25, v25
	v_mul_f32_e32 v3, v3, v16
	v_mul_f32_e32 v9, v9, v17
	v_mul_f32_e32 v13, v13, v18
	v_mul_f32_e32 v11, v11, v19
	v_mul_f32_e32 v15, v15, v22
	v_mul_f32_e32 v5, v5, v23
	v_mul_f32_e32 v1, v1, v24
	v_mul_f32_e32 v7, v7, v25
	v_mul_f32_e32 v2, v2, v3
	v_mul_f32_e32 v3, v8, v9
	v_mul_f32_e32 v8, v12, v13
	v_mul_f32_e32 v9, v10, v11
	v_mul_f32_e32 v10, v14, v15
	v_mul_f32_e32 v4, v4, v5
	v_mul_f32_e32 v5, v0, v1
	v_mul_f32_e32 v6, v6, v7
	v_cvt_pk_bf16_f32 v0, v2, v3
	v_cvt_pk_bf16_f32 v1, v8, v9
	v_cvt_pk_bf16_f32 v2, v10, v4
	v_cvt_pk_bf16_f32 v3, v5, v6
	global_store_dwordx4 v[20:21], v[0:3], off
	s_cbranch_vccnz .LBB0_1304
	s_andn2_b64 vcc, exec, s[14:15]
	s_cbranch_vccnz .LBB0_1303
	s_barrier
	s_branch .LBB0_1303
